# P0 weight-transpose load loops fully unrolled: 32 loads in flight per item with counted vmcnt (on top of rms-epilogue pipelining)
# speedup vs baseline: 1.0010x; 1.0010x over previous
; #define LDS_WAIT() asm volatile("s_waitcnt lgkmcnt(0)" ::: "memory")
; #pragma unroll 8
;     for (int i = 0; i < 32; ++i) { const int kk = 2 * i + (lane >> 5); scr[kk * 33 + (lane & 31)] = __builtin_nontemporal_load(W + (size_t)(k0 + kk) * N + n0 + (lane & 31)); }
;     LDS_WAIT(); asm volatile("" ::: "memory");
.LBB0_11:
	v_lshl_add_u64 v[34:35], v[32:33], 0, s[4:5]
	v_lshl_add_u64 v[36:37], v[30:31], 0, s[4:5]
	v_lshl_add_u64 v[38:39], v[28:29], 0, s[4:5]
	v_lshl_add_u64 v[40:41], v[26:27], 0, s[4:5]
	v_lshl_add_u64 v[42:43], v[24:25], 0, s[4:5]
	v_lshl_add_u64 v[44:45], v[22:23], 0, s[4:5]
	v_lshl_add_u64 v[70:71], v[20:21], 0, s[4:5]
	v_lshl_add_u64 v[72:73], v[18:19], 0, s[4:5]
	global_load_dword v86, v[34:35], off nt
	global_load_dword v87, v[36:37], off nt
	global_load_dword v88, v[38:39], off nt
	global_load_dword v89, v[40:41], off nt
	global_load_dword v90, v[42:43], off nt
	global_load_dword v91, v[44:45], off nt
	global_load_dword v92, v[70:71], off nt
	global_load_dword v93, v[72:73], off nt
	s_add_u32 s4, s4, 0x20000
	s_addc_u32 s5, s5, 0
	s_cmp_lg_u32 s4, 0x80000
	v_lshl_add_u64 v[34:35], v[32:33], 0, s[4:5]
	v_lshl_add_u64 v[36:37], v[30:31], 0, s[4:5]
	v_lshl_add_u64 v[38:39], v[28:29], 0, s[4:5]
	v_lshl_add_u64 v[40:41], v[26:27], 0, s[4:5]
	v_lshl_add_u64 v[42:43], v[24:25], 0, s[4:5]
	v_lshl_add_u64 v[44:45], v[22:23], 0, s[4:5]
	v_lshl_add_u64 v[70:71], v[20:21], 0, s[4:5]
	v_lshl_add_u64 v[72:73], v[18:19], 0, s[4:5]
	global_load_dword v94, v[34:35], off nt
	global_load_dword v95, v[36:37], off nt
	global_load_dword v96, v[38:39], off nt
	global_load_dword v97, v[40:41], off nt
	global_load_dword v98, v[42:43], off nt
	global_load_dword v99, v[44:45], off nt
	global_load_dword v100, v[70:71], off nt
	global_load_dword v101, v[72:73], off nt
	s_add_u32 s4, s4, 0x20000
	s_addc_u32 s5, s5, 0
	s_cmp_lg_u32 s4, 0x80000
	v_lshl_add_u64 v[34:35], v[32:33], 0, s[4:5]
	v_lshl_add_u64 v[36:37], v[30:31], 0, s[4:5]
	v_lshl_add_u64 v[38:39], v[28:29], 0, s[4:5]
	v_lshl_add_u64 v[40:41], v[26:27], 0, s[4:5]
	v_lshl_add_u64 v[42:43], v[24:25], 0, s[4:5]
	v_lshl_add_u64 v[44:45], v[22:23], 0, s[4:5]
	v_lshl_add_u64 v[70:71], v[20:21], 0, s[4:5]
	v_lshl_add_u64 v[72:73], v[18:19], 0, s[4:5]
	global_load_dword v102, v[34:35], off nt
	global_load_dword v103, v[36:37], off nt
	global_load_dword v104, v[38:39], off nt
	global_load_dword v105, v[40:41], off nt
	global_load_dword v106, v[42:43], off nt
	global_load_dword v107, v[44:45], off nt
	global_load_dword v108, v[70:71], off nt
	global_load_dword v109, v[72:73], off nt
	s_add_u32 s4, s4, 0x20000
	s_addc_u32 s5, s5, 0
	s_cmp_lg_u32 s4, 0x80000
	v_lshl_add_u64 v[34:35], v[32:33], 0, s[4:5]
	v_lshl_add_u64 v[36:37], v[30:31], 0, s[4:5]
	v_lshl_add_u64 v[38:39], v[28:29], 0, s[4:5]
	v_lshl_add_u64 v[40:41], v[26:27], 0, s[4:5]
	v_lshl_add_u64 v[42:43], v[24:25], 0, s[4:5]
	v_lshl_add_u64 v[44:45], v[22:23], 0, s[4:5]
	v_lshl_add_u64 v[70:71], v[20:21], 0, s[4:5]
	v_lshl_add_u64 v[72:73], v[18:19], 0, s[4:5]
	global_load_dword v110, v[34:35], off nt
	global_load_dword v111, v[36:37], off nt
	global_load_dword v112, v[38:39], off nt
	global_load_dword v113, v[40:41], off nt
	global_load_dword v114, v[42:43], off nt
	global_load_dword v115, v[44:45], off nt
	global_load_dword v116, v[70:71], off nt
	global_load_dword v117, v[72:73], off nt
	s_add_u32 s4, s4, 0x20000
	s_addc_u32 s5, s5, 0
	s_cmp_lg_u32 s4, 0x80000
	v_add_u32_e32 v41, 0x400, v2
	s_waitcnt vmcnt(30)
	ds_write2_b32 v2, v86, v87 offset1:66
	s_waitcnt vmcnt(28)
	ds_write2_b32 v2, v88, v89 offset0:132 offset1:198
	s_waitcnt vmcnt(26)
	ds_write2_b32 v41, v90, v91 offset0:8 offset1:74
	s_waitcnt vmcnt(24)
	ds_write2_b32 v41, v92, v93 offset0:140 offset1:206
	v_add_u32_e32 v2, 0x840, v2
	v_add_u32_e32 v41, 0x400, v2
	s_waitcnt vmcnt(22)
	ds_write2_b32 v2, v94, v95 offset1:66
	s_waitcnt vmcnt(20)
	ds_write2_b32 v2, v96, v97 offset0:132 offset1:198
	s_waitcnt vmcnt(18)
	ds_write2_b32 v41, v98, v99 offset0:8 offset1:74
	s_waitcnt vmcnt(16)
	ds_write2_b32 v41, v100, v101 offset0:140 offset1:206
	v_add_u32_e32 v2, 0x840, v2
	v_add_u32_e32 v41, 0x400, v2
	s_waitcnt vmcnt(14)
	ds_write2_b32 v2, v102, v103 offset1:66
	s_waitcnt vmcnt(12)
	ds_write2_b32 v2, v104, v105 offset0:132 offset1:198
	s_waitcnt vmcnt(10)
	ds_write2_b32 v41, v106, v107 offset0:8 offset1:74
	s_waitcnt vmcnt(8)
	ds_write2_b32 v41, v108, v109 offset0:140 offset1:206
	v_add_u32_e32 v2, 0x840, v2
	v_add_u32_e32 v41, 0x400, v2
	s_waitcnt vmcnt(6)
	ds_write2_b32 v2, v110, v111 offset1:66
	s_waitcnt vmcnt(4)
	ds_write2_b32 v2, v112, v113 offset0:132 offset1:198
	s_waitcnt vmcnt(2)
	ds_write2_b32 v41, v114, v115 offset0:8 offset1:74
	s_waitcnt vmcnt(0)
	ds_write2_b32 v41, v116, v117 offset0:140 offset1:206
	v_add_u32_e32 v2, 0x840, v2
	s_waitcnt lgkmcnt(0)
; #define LAS __attribute__((address_space(3)))
; __device__ __forceinline__ unsigned pk2(float lo, float hi) { return f2bf(lo) | (f2bf(hi) << 16); }
; #define LDS_WAIT() asm volatile("s_waitcnt lgkmcnt(0)" ::: "memory")
;     ...
;     LDS_WAIT(); asm volatile("" ::: "memory");
;     const int c = lane & 7;
; #pragma unroll
;     for (int j = 0; j < 4; ++j) { const int n = (lane >> 3) + 8 * j; const LAS float* s = scr + (8 * c) * 33 + n;
;         u32x4v o; o.x = pk2(s[0 * 33], s[1 * 33]); o.y = pk2(s[2 * 33], s[3 * 33]); o.z = pk2(s[4 * 33], s[5 * 33]); o.w = pk2(s[6 * 33], s[7 * 33]);
;         *(u32x4v*)(WT + (size_t)(drow0 + dstride * n) * K + k0 + 8 * c) = o; }
;     LDS_WAIT(); asm volatile("" ::: "memory");
	ds_read2_b32 v[22:23], v46 offset1:8
	ds_read2_b32 v[26:27], v46 offset0:33 offset1:41
	ds_read2_b32 v[28:29], v46 offset0:66 offset1:74
	ds_read2_b32 v[30:31], v46 offset0:99 offset1:107
	ds_read2_b32 v[32:33], v46 offset0:132 offset1:140
	s_waitcnt lgkmcnt(4)
	v_bfe_u32 v2, v22, 16, 1
	v_add3_u32 v2, v22, v2, s29
	s_waitcnt lgkmcnt(3)
	v_bfe_u32 v17, v26, 16, 1
	v_lshrrev_b32_e32 v2, 16, v2
	v_add3_u32 v17, v26, v17, s29
	ds_read2_b32 v[34:35], v46 offset0:165 offset1:173
	v_and_or_b32 v18, v17, s34, v2
	s_waitcnt lgkmcnt(3)
	v_bfe_u32 v2, v28, 16, 1
	v_add3_u32 v2, v28, v2, s29
	s_waitcnt lgkmcnt(2)
	v_bfe_u32 v17, v30, 16, 1
	ds_read2_b32 v[36:37], v46 offset0:198 offset1:206
	v_lshrrev_b32_e32 v2, 16, v2
	v_add3_u32 v17, v30, v17, s29
	ds_read2_b32 v[38:39], v46 offset0:231 offset1:239
	v_and_or_b32 v19, v17, s34, v2
	s_waitcnt lgkmcnt(3)
	v_bfe_u32 v2, v32, 16, 1
	v_add3_u32 v2, v32, v2, s29
	s_waitcnt lgkmcnt(2)
	v_bfe_u32 v17, v34, 16, 1
	v_lshrrev_b32_e32 v2, 16, v2
	v_add3_u32 v17, v34, v17, s29
	v_and_or_b32 v20, v17, s34, v2
	s_waitcnt lgkmcnt(1)
	v_bfe_u32 v2, v36, 16, 1
	s_lshl_b32 s4, s77, 5
	v_add3_u32 v2, v36, v2, s29
	s_waitcnt lgkmcnt(0)
	v_bfe_u32 v17, v38, 16, 1
	s_and_b32 s4, s4, 0x7e0
	v_lshrrev_b32_e32 v2, 16, v2
	v_add3_u32 v17, v38, v17, s29
	s_add_i32 s0, s0, 0xffff6a00
	v_and_or_b32 v21, v17, s34, v2
	v_or_b32_e32 v2, s4, v5
	v_lshl_add_u64 v[24:25], s[0:1], 1, v[6:7]
	v_lshlrev_b32_e32 v2, 12, v2
	v_lshl_add_u64 v[40:41], v[24:25], 0, v[2:3]
	v_bfe_u32 v2, v23, 16, 1
	v_add3_u32 v2, v23, v2, s29
	v_bfe_u32 v17, v27, 16, 1
	v_lshrrev_b32_e32 v2, 16, v2
	v_add3_u32 v17, v27, v17, s29
	global_store_dwordx4 v[40:41], v[18:21], off
	ds_read2_b32 v[22:23], v46 offset0:16 offset1:24
	s_nop 0
	v_and_or_b32 v18, v17, s34, v2
	v_bfe_u32 v2, v29, 16, 1
	v_add3_u32 v2, v29, v2, s29
	v_bfe_u32 v17, v31, 16, 1
	v_lshrrev_b32_e32 v2, 16, v2
	v_add3_u32 v17, v31, v17, s29
	v_and_or_b32 v19, v17, s34, v2
	v_bfe_u32 v2, v33, 16, 1
	v_add3_u32 v2, v33, v2, s29
	v_bfe_u32 v17, v35, 16, 1
	v_lshrrev_b32_e32 v2, 16, v2
	v_add3_u32 v17, v35, v17, s29
	v_and_or_b32 v20, v17, s34, v2
	v_bfe_u32 v2, v37, 16, 1
	v_add3_u32 v2, v37, v2, s29
	v_bfe_u32 v17, v39, 16, 1
	v_lshrrev_b32_e32 v2, 16, v2
	v_add3_u32 v17, v39, v17, s29
	v_and_or_b32 v21, v17, s34, v2
	v_or_b32_e32 v2, s4, v47
	v_lshlrev_b32_e32 v2, 12, v2
	v_lshl_add_u64 v[26:27], v[24:25], 0, v[2:3]
	global_store_dwordx4 v[26:27], v[18:21], off
	ds_read2_b32 v[26:27], v46 offset0:49 offset1:57
	ds_read2_b32 v[28:29], v46 offset0:82 offset1:90
	ds_read2_b32 v[30:31], v46 offset0:115 offset1:123
	s_waitcnt lgkmcnt(3)
	v_bfe_u32 v2, v22, 16, 1
	v_add3_u32 v2, v22, v2, s29
	s_waitcnt lgkmcnt(2)
	v_bfe_u32 v17, v26, 16, 1
	ds_read2_b32 v[32:33], v46 offset0:148 offset1:156
	v_lshrrev_b32_e32 v2, 16, v2
	v_add3_u32 v17, v26, v17, s29
	ds_read2_b32 v[34:35], v46 offset0:181 offset1:189
	v_and_or_b32 v18, v17, s34, v2
	s_waitcnt lgkmcnt(3)
	v_bfe_u32 v2, v28, 16, 1
	v_add3_u32 v2, v28, v2, s29
	s_waitcnt lgkmcnt(2)
	v_bfe_u32 v17, v30, 16, 1
	ds_read2_b32 v[36:37], v46 offset0:214 offset1:222
	v_lshrrev_b32_e32 v2, 16, v2
	v_add3_u32 v17, v30, v17, s29
	ds_read2_b32 v[38:39], v46 offset0:247 offset1:255
	v_and_or_b32 v19, v17, s34, v2
	s_waitcnt lgkmcnt(3)
	v_bfe_u32 v2, v32, 16, 1
	v_add3_u32 v2, v32, v2, s29
	s_waitcnt lgkmcnt(2)
	v_bfe_u32 v17, v34, 16, 1
	v_lshrrev_b32_e32 v2, 16, v2
	v_add3_u32 v17, v34, v17, s29
	v_and_or_b32 v20, v17, s34, v2
	s_waitcnt lgkmcnt(1)
	v_bfe_u32 v2, v36, 16, 1
	v_add3_u32 v2, v36, v2, s29
	s_waitcnt lgkmcnt(0)
	v_bfe_u32 v17, v38, 16, 1
	v_lshrrev_b32_e32 v2, 16, v2
	v_add3_u32 v17, v38, v17, s29
	v_and_or_b32 v21, v17, s34, v2
	v_or_b32_e32 v2, s4, v48
	v_lshlrev_b32_e32 v2, 12, v2
	v_lshl_add_u64 v[40:41], v[24:25], 0, v[2:3]
	v_bfe_u32 v2, v23, 16, 1
	v_add3_u32 v2, v23, v2, s29
	v_bfe_u32 v17, v27, 16, 1
	v_lshrrev_b32_e32 v2, 16, v2
	v_add3_u32 v17, v27, v17, s29
	global_store_dwordx4 v[40:41], v[18:21], off
	s_nop 1
	v_and_or_b32 v18, v17, s34, v2
	v_bfe_u32 v2, v29, 16, 1
	v_add3_u32 v2, v29, v2, s29
	v_bfe_u32 v17, v31, 16, 1
	v_lshrrev_b32_e32 v2, 16, v2
	v_add3_u32 v17, v31, v17, s29
	v_and_or_b32 v19, v17, s34, v2
	v_bfe_u32 v2, v33, 16, 1
	v_add3_u32 v2, v33, v2, s29
	v_bfe_u32 v17, v35, 16, 1
	v_lshrrev_b32_e32 v2, 16, v2
	v_add3_u32 v17, v35, v17, s29
	v_and_or_b32 v20, v17, s34, v2
	v_bfe_u32 v2, v37, 16, 1
	v_add3_u32 v2, v37, v2, s29
	v_bfe_u32 v17, v39, 16, 1
	v_lshrrev_b32_e32 v2, 16, v2
	v_add3_u32 v17, v39, v17, s29
	v_and_or_b32 v21, v17, s34, v2
	v_or_b32_e32 v2, s4, v49
	v_lshlrev_b32_e32 v2, 12, v2
	v_lshl_add_u64 v[22:23], v[24:25], 0, v[2:3]
	global_store_dwordx4 v[22:23], v[18:21], off
	s_waitcnt lgkmcnt(0)
	s_mov_b64 s[4:5], 0

; #define LDS_WAIT() asm volatile("s_waitcnt lgkmcnt(0)" ::: "memory")
; #pragma unroll 8
;     for (int i = 0; i < 32; ++i) { const int kk = 2 * i + (lane >> 5); scr[kk * 33 + (lane & 31)] = __builtin_nontemporal_load(W + (size_t)(k0 + kk) * N + n0 + (lane & 31)); }
;     LDS_WAIT(); asm volatile("" ::: "memory");
.LBB0_16:
	v_lshl_add_u64 v[70:71], v[44:45], 0, s[4:5]
	v_lshl_add_u64 v[72:73], v[42:43], 0, s[4:5]
	v_lshl_add_u64 v[74:75], v[40:41], 0, s[4:5]
	v_lshl_add_u64 v[76:77], v[38:39], 0, s[4:5]
	v_lshl_add_u64 v[78:79], v[36:37], 0, s[4:5]
	v_lshl_add_u64 v[80:81], v[34:35], 0, s[4:5]
	v_lshl_add_u64 v[82:83], v[32:33], 0, s[4:5]
	v_lshl_add_u64 v[84:85], v[30:31], 0, s[4:5]
	global_load_dword v86, v[70:71], off nt
	global_load_dword v87, v[72:73], off nt
	global_load_dword v88, v[74:75], off nt
	global_load_dword v89, v[76:77], off nt
	global_load_dword v90, v[78:79], off nt
	global_load_dword v91, v[80:81], off nt
	global_load_dword v92, v[82:83], off nt
	global_load_dword v93, v[84:85], off nt
	s_add_u32 s4, s4, 0x48000
	s_addc_u32 s5, s5, 0
	s_cmp_lg_u32 s4, 0x120000
	v_lshl_add_u64 v[70:71], v[44:45], 0, s[4:5]
	v_lshl_add_u64 v[72:73], v[42:43], 0, s[4:5]
	v_lshl_add_u64 v[74:75], v[40:41], 0, s[4:5]
	v_lshl_add_u64 v[76:77], v[38:39], 0, s[4:5]
	v_lshl_add_u64 v[78:79], v[36:37], 0, s[4:5]
	v_lshl_add_u64 v[80:81], v[34:35], 0, s[4:5]
	v_lshl_add_u64 v[82:83], v[32:33], 0, s[4:5]
	v_lshl_add_u64 v[84:85], v[30:31], 0, s[4:5]
	global_load_dword v94, v[70:71], off nt
	global_load_dword v95, v[72:73], off nt
	global_load_dword v96, v[74:75], off nt
	global_load_dword v97, v[76:77], off nt
	global_load_dword v98, v[78:79], off nt
	global_load_dword v99, v[80:81], off nt
	global_load_dword v100, v[82:83], off nt
	global_load_dword v101, v[84:85], off nt
	s_add_u32 s4, s4, 0x48000
	s_addc_u32 s5, s5, 0
	s_cmp_lg_u32 s4, 0x120000
	v_lshl_add_u64 v[70:71], v[44:45], 0, s[4:5]
	v_lshl_add_u64 v[72:73], v[42:43], 0, s[4:5]
	v_lshl_add_u64 v[74:75], v[40:41], 0, s[4:5]
	v_lshl_add_u64 v[76:77], v[38:39], 0, s[4:5]
	v_lshl_add_u64 v[78:79], v[36:37], 0, s[4:5]
	v_lshl_add_u64 v[80:81], v[34:35], 0, s[4:5]
	v_lshl_add_u64 v[82:83], v[32:33], 0, s[4:5]
	v_lshl_add_u64 v[84:85], v[30:31], 0, s[4:5]
	global_load_dword v102, v[70:71], off nt
	global_load_dword v103, v[72:73], off nt
	global_load_dword v104, v[74:75], off nt
	global_load_dword v105, v[76:77], off nt
	global_load_dword v106, v[78:79], off nt
	global_load_dword v107, v[80:81], off nt
	global_load_dword v108, v[82:83], off nt
	global_load_dword v109, v[84:85], off nt
	s_add_u32 s4, s4, 0x48000
	s_addc_u32 s5, s5, 0
	s_cmp_lg_u32 s4, 0x120000
	v_lshl_add_u64 v[70:71], v[44:45], 0, s[4:5]
	v_lshl_add_u64 v[72:73], v[42:43], 0, s[4:5]
	v_lshl_add_u64 v[74:75], v[40:41], 0, s[4:5]
	v_lshl_add_u64 v[76:77], v[38:39], 0, s[4:5]
	v_lshl_add_u64 v[78:79], v[36:37], 0, s[4:5]
	v_lshl_add_u64 v[80:81], v[34:35], 0, s[4:5]
	v_lshl_add_u64 v[82:83], v[32:33], 0, s[4:5]
	v_lshl_add_u64 v[84:85], v[30:31], 0, s[4:5]
	global_load_dword v110, v[70:71], off nt
	global_load_dword v111, v[72:73], off nt
	global_load_dword v112, v[74:75], off nt
	global_load_dword v113, v[76:77], off nt
	global_load_dword v114, v[78:79], off nt
	global_load_dword v115, v[80:81], off nt
	global_load_dword v116, v[82:83], off nt
	global_load_dword v117, v[84:85], off nt
	s_add_u32 s4, s4, 0x48000
	s_addc_u32 s5, s5, 0
	s_cmp_lg_u32 s4, 0x120000
	v_add_u32_e32 v73, 0x400, v19
	s_waitcnt vmcnt(30)
	ds_write2_b32 v19, v86, v87 offset1:66
	s_waitcnt vmcnt(28)
	ds_write2_b32 v19, v88, v89 offset0:132 offset1:198
	s_waitcnt vmcnt(26)
	ds_write2_b32 v73, v90, v91 offset0:8 offset1:74
	s_waitcnt vmcnt(24)
	ds_write2_b32 v73, v92, v93 offset0:140 offset1:206
	v_add_u32_e32 v19, 0x840, v19
	v_add_u32_e32 v73, 0x400, v19
	s_waitcnt vmcnt(22)
	ds_write2_b32 v19, v94, v95 offset1:66
	s_waitcnt vmcnt(20)
	ds_write2_b32 v19, v96, v97 offset0:132 offset1:198
	s_waitcnt vmcnt(18)
	ds_write2_b32 v73, v98, v99 offset0:8 offset1:74
	s_waitcnt vmcnt(16)
	ds_write2_b32 v73, v100, v101 offset0:140 offset1:206
	v_add_u32_e32 v19, 0x840, v19
	v_add_u32_e32 v73, 0x400, v19
	s_waitcnt vmcnt(14)
	ds_write2_b32 v19, v102, v103 offset1:66
	s_waitcnt vmcnt(12)
	ds_write2_b32 v19, v104, v105 offset0:132 offset1:198
	s_waitcnt vmcnt(10)
	ds_write2_b32 v73, v106, v107 offset0:8 offset1:74
	s_waitcnt vmcnt(8)
	ds_write2_b32 v73, v108, v109 offset0:140 offset1:206
	v_add_u32_e32 v19, 0x840, v19
	v_add_u32_e32 v73, 0x400, v19
	s_waitcnt vmcnt(6)
	ds_write2_b32 v19, v110, v111 offset1:66
	s_waitcnt vmcnt(4)
	ds_write2_b32 v19, v112, v113 offset0:132 offset1:198
	s_waitcnt vmcnt(2)
	ds_write2_b32 v73, v114, v115 offset0:8 offset1:74
	s_waitcnt vmcnt(0)
	ds_write2_b32 v73, v116, v117 offset0:140 offset1:206
	v_add_u32_e32 v19, 0x840, v19
	s_waitcnt lgkmcnt(0)
	ds_read2_b32 v[34:35], v46 offset1:8
	ds_read2_b32 v[38:39], v46 offset0:33 offset1:41
	ds_read2_b32 v[40:41], v46 offset0:66 offset1:74
	ds_read2_b32 v[42:43], v46 offset0:99 offset1:107
	ds_read2_b32 v[44:45], v46 offset0:132 offset1:140
	ds_read2_b32 v[70:71], v46 offset0:165 offset1:173
	s_waitcnt lgkmcnt(5)
; #define LAS __attribute__((address_space(3)))
; __device__ __forceinline__ unsigned pk2(float lo, float hi) { return f2bf(lo) | (f2bf(hi) << 16); }
;     ...
;     const int c = lane & 7;
; #pragma unroll
;     for (int j = 0; j < 4; ++j) { const int n = (lane >> 3) + 8 * j; const LAS float* s = scr + (8 * c) * 33 + n;
;         u32x4v o; o.x = pk2(s[0 * 33], s[1 * 33]); o.y = pk2(s[2 * 33], s[3 * 33]); o.z = pk2(s[4 * 33], s[5 * 33]); o.w = pk2(s[6 * 33], s[7 * 33]);
;         *(u32x4v*)(WT + (size_t)(drow0 + dstride * n) * K + k0 + 8 * c) = o; }
	v_bfe_u32 v19, v34, 16, 1
	v_add3_u32 v19, v34, v19, s29
	s_waitcnt lgkmcnt(4)
	v_bfe_u32 v21, v38, 16, 1
	v_lshrrev_b32_e32 v19, 16, v19
	v_add3_u32 v21, v38, v21, s29
	v_and_or_b32 v30, v21, s34, v19
	s_waitcnt lgkmcnt(3)
	v_bfe_u32 v19, v40, 16, 1
	v_add3_u32 v19, v40, v19, s29
	s_waitcnt lgkmcnt(2)
	v_bfe_u32 v21, v42, 16, 1
	ds_read2_b32 v[72:73], v46 offset0:198 offset1:206
	v_lshrrev_b32_e32 v19, 16, v19
	v_add3_u32 v21, v42, v21, s29
	ds_read2_b32 v[74:75], v46 offset0:231 offset1:239
	v_and_or_b32 v31, v21, s34, v19
	s_waitcnt lgkmcnt(3)
	v_bfe_u32 v19, v44, 16, 1
	v_add3_u32 v19, v44, v19, s29
	s_waitcnt lgkmcnt(2)
	v_bfe_u32 v21, v70, 16, 1
	v_lshrrev_b32_e32 v19, 16, v19
	v_add3_u32 v21, v70, v21, s29
	v_and_or_b32 v32, v21, s34, v19
	s_waitcnt lgkmcnt(1)
	v_bfe_u32 v19, v72, 16, 1
	v_add3_u32 v19, v72, v19, s29
	s_waitcnt lgkmcnt(0)
	v_bfe_u32 v21, v74, 16, 1
	v_lshrrev_b32_e32 v19, 16, v19
	v_add3_u32 v21, v74, v21, s29
	v_and_or_b32 v33, v21, s34, v19
	v_or_b32_e32 v19, s10, v5
	s_lshl_b32 s0, s6, 1
	v_lshlrev_b32_e32 v76, 12, v19
	v_bfe_u32 v19, v35, 16, 1
	v_lshl_add_u64 v[36:37], v[8:9], 0, s[0:1]
	v_mov_b32_e32 v77, v3
	v_add3_u32 v19, v35, v19, s29
	v_bfe_u32 v21, v39, 16, 1
	v_lshl_add_u64 v[76:77], v[36:37], 0, v[76:77]
	v_lshrrev_b32_e32 v19, 16, v19
	v_add3_u32 v21, v39, v21, s29
	global_store_dwordx4 v[76:77], v[30:33], off
	v_mov_b32_e32 v35, v3
	ds_read2_b32 v[38:39], v46 offset0:16 offset1:24
	v_and_or_b32 v30, v21, s34, v19
	v_bfe_u32 v19, v41, 16, 1
	v_add3_u32 v19, v41, v19, s29
	v_bfe_u32 v21, v43, 16, 1
	v_lshrrev_b32_e32 v19, 16, v19
	v_add3_u32 v21, v43, v21, s29
	v_and_or_b32 v31, v21, s34, v19
	v_bfe_u32 v19, v45, 16, 1
	v_add3_u32 v19, v45, v19, s29
	v_bfe_u32 v21, v71, 16, 1
	v_lshrrev_b32_e32 v19, 16, v19
	v_add3_u32 v21, v71, v21, s29
	v_and_or_b32 v32, v21, s34, v19
	v_bfe_u32 v19, v73, 16, 1
	v_add3_u32 v19, v73, v19, s29
	v_bfe_u32 v21, v75, 16, 1
	v_lshrrev_b32_e32 v19, 16, v19
	v_add3_u32 v21, v75, v21, s29
	v_and_or_b32 v33, v21, s34, v19
	v_or_b32_e32 v19, s10, v47
	v_lshlrev_b32_e32 v34, 12, v19
	v_lshl_add_u64 v[34:35], v[36:37], 0, v[34:35]
	global_store_dwordx4 v[34:35], v[30:33], off
	ds_read2_b32 v[34:35], v46 offset0:49 offset1:57
	ds_read2_b32 v[40:41], v46 offset0:82 offset1:90
	ds_read2_b32 v[42:43], v46 offset0:115 offset1:123
	s_waitcnt lgkmcnt(3)
	v_bfe_u32 v19, v38, 16, 1
	v_add3_u32 v19, v38, v19, s29
	s_waitcnt lgkmcnt(2)
	v_bfe_u32 v21, v34, 16, 1
	ds_read2_b32 v[44:45], v46 offset0:148 offset1:156
	v_lshrrev_b32_e32 v19, 16, v19
	v_add3_u32 v21, v34, v21, s29
	ds_read2_b32 v[70:71], v46 offset0:181 offset1:189
	v_and_or_b32 v30, v21, s34, v19
	s_waitcnt lgkmcnt(3)
	v_bfe_u32 v19, v40, 16, 1
	v_add3_u32 v19, v40, v19, s29
	s_waitcnt lgkmcnt(2)
	v_bfe_u32 v21, v42, 16, 1
	ds_read2_b32 v[72:73], v46 offset0:214 offset1:222
	v_lshrrev_b32_e32 v19, 16, v19
	v_add3_u32 v21, v42, v21, s29
	ds_read2_b32 v[74:75], v46 offset0:247 offset1:255
	v_and_or_b32 v31, v21, s34, v19
	s_waitcnt lgkmcnt(3)
	v_bfe_u32 v19, v44, 16, 1
	v_add3_u32 v19, v44, v19, s29
	s_waitcnt lgkmcnt(2)
	v_bfe_u32 v21, v70, 16, 1
	v_lshrrev_b32_e32 v19, 16, v19
	v_add3_u32 v21, v70, v21, s29
	v_and_or_b32 v32, v21, s34, v19
	s_waitcnt lgkmcnt(1)
	v_bfe_u32 v19, v72, 16, 1
	v_add3_u32 v19, v72, v19, s29
	s_waitcnt lgkmcnt(0)
	v_bfe_u32 v21, v74, 16, 1
	v_lshrrev_b32_e32 v19, 16, v19
	v_add3_u32 v21, v74, v21, s29
	v_and_or_b32 v33, v21, s34, v19
	v_or_b32_e32 v19, s10, v48
	v_lshlrev_b32_e32 v76, 12, v19
	v_bfe_u32 v19, v39, 16, 1
	v_mov_b32_e32 v77, v3
	v_add3_u32 v19, v39, v19, s29
	v_bfe_u32 v21, v35, 16, 1
	v_lshl_add_u64 v[76:77], v[36:37], 0, v[76:77]
	v_lshrrev_b32_e32 v19, 16, v19
	v_add3_u32 v21, v35, v21, s29
	global_store_dwordx4 v[76:77], v[30:33], off
	v_mov_b32_e32 v35, v3
	s_mov_b64 s[4:5], 0
	v_and_or_b32 v30, v21, s34, v19
	v_bfe_u32 v19, v41, 16, 1
	v_add3_u32 v19, v41, v19, s29
	v_bfe_u32 v21, v43, 16, 1
	v_lshrrev_b32_e32 v19, 16, v19
	v_add3_u32 v21, v43, v21, s29
	v_and_or_b32 v31, v21, s34, v19
	v_bfe_u32 v19, v45, 16, 1
	v_add3_u32 v19, v45, v19, s29
	v_bfe_u32 v21, v71, 16, 1
	v_lshrrev_b32_e32 v19, 16, v19
	v_add3_u32 v21, v71, v21, s29
	v_and_or_b32 v32, v21, s34, v19
	v_bfe_u32 v19, v73, 16, 1
	v_add3_u32 v19, v73, v19, s29
	v_bfe_u32 v21, v75, 16, 1
	v_lshrrev_b32_e32 v19, 16, v19
	v_add3_u32 v21, v75, v21, s29
	v_and_or_b32 v33, v21, s34, v19
	v_or_b32_e32 v19, s10, v49
	v_lshlrev_b32_e32 v34, 12, v19
	v_lshl_add_u64 v[34:35], v[36:37], 0, v[34:35]
	global_store_dwordx4 v[34:35], v[30:33], off
	s_waitcnt lgkmcnt(0)

; #define LDS_WAIT() asm volatile("s_waitcnt lgkmcnt(0)" ::: "memory")
; #pragma unroll 8
;     for (int i = 0; i < 32; ++i) { const int kk = 2 * i + (lane >> 5); scr[kk * 33 + (lane & 31)] = __builtin_nontemporal_load(W + (size_t)(k0 + kk) * N + n0 + (lane & 31)); }
;     LDS_WAIT(); asm volatile("" ::: "memory");
; __global__ void __launch_bounds__(NTHR, 2) fwd_kernel(Args args) {
;     ...
;                 if (n0 < 1280) { const int hh = n0 >> 7, d0 = n0 & 127; transpose_item(w_in, DM, NIN, WIN, 64 * kb, n0, hh * 128 + (d0 & 64) + ((d0 & 63) >> 5), scr, lane, 2); }
.LBB0_20:
	v_lshl_add_u64 v[34:35], v[32:33], 0, s[4:5]
	v_lshl_add_u64 v[36:37], v[18:19], 0, s[4:5]
	v_lshl_add_u64 v[38:39], v[20:21], 0, s[4:5]
	v_lshl_add_u64 v[40:41], v[22:23], 0, s[4:5]
	v_lshl_add_u64 v[42:43], v[24:25], 0, s[4:5]
	v_lshl_add_u64 v[44:45], v[26:27], 0, s[4:5]
	v_lshl_add_u64 v[70:71], v[28:29], 0, s[4:5]
	v_lshl_add_u64 v[72:73], v[30:31], 0, s[4:5]
	global_load_dword v86, v[34:35], off nt
	global_load_dword v87, v[36:37], off nt
	global_load_dword v88, v[38:39], off nt
	global_load_dword v89, v[40:41], off nt
	global_load_dword v90, v[42:43], off nt
	global_load_dword v91, v[44:45], off nt
	global_load_dword v92, v[70:71], off nt
	global_load_dword v93, v[72:73], off nt
	s_add_u32 s4, s4, 0x48000
	s_addc_u32 s5, s5, 0
	s_cmp_lg_u32 s4, 0x120000
	v_lshl_add_u64 v[34:35], v[32:33], 0, s[4:5]
	v_lshl_add_u64 v[36:37], v[18:19], 0, s[4:5]
	v_lshl_add_u64 v[38:39], v[20:21], 0, s[4:5]
	v_lshl_add_u64 v[40:41], v[22:23], 0, s[4:5]
	v_lshl_add_u64 v[42:43], v[24:25], 0, s[4:5]
	v_lshl_add_u64 v[44:45], v[26:27], 0, s[4:5]
	v_lshl_add_u64 v[70:71], v[28:29], 0, s[4:5]
	v_lshl_add_u64 v[72:73], v[30:31], 0, s[4:5]
	global_load_dword v94, v[34:35], off nt
	global_load_dword v95, v[36:37], off nt
	global_load_dword v96, v[38:39], off nt
	global_load_dword v97, v[40:41], off nt
	global_load_dword v98, v[42:43], off nt
	global_load_dword v99, v[44:45], off nt
	global_load_dword v100, v[70:71], off nt
	global_load_dword v101, v[72:73], off nt
	s_add_u32 s4, s4, 0x48000
	s_addc_u32 s5, s5, 0
	s_cmp_lg_u32 s4, 0x120000
	v_lshl_add_u64 v[34:35], v[32:33], 0, s[4:5]
	v_lshl_add_u64 v[36:37], v[18:19], 0, s[4:5]
	v_lshl_add_u64 v[38:39], v[20:21], 0, s[4:5]
	v_lshl_add_u64 v[40:41], v[22:23], 0, s[4:5]
	v_lshl_add_u64 v[42:43], v[24:25], 0, s[4:5]
	v_lshl_add_u64 v[44:45], v[26:27], 0, s[4:5]
	v_lshl_add_u64 v[70:71], v[28:29], 0, s[4:5]
	v_lshl_add_u64 v[72:73], v[30:31], 0, s[4:5]
	global_load_dword v102, v[34:35], off nt
	global_load_dword v103, v[36:37], off nt
	global_load_dword v104, v[38:39], off nt
	global_load_dword v105, v[40:41], off nt
	global_load_dword v106, v[42:43], off nt
	global_load_dword v107, v[44:45], off nt
	global_load_dword v108, v[70:71], off nt
	global_load_dword v109, v[72:73], off nt
	s_add_u32 s4, s4, 0x48000
	s_addc_u32 s5, s5, 0
	s_cmp_lg_u32 s4, 0x120000
	v_lshl_add_u64 v[34:35], v[32:33], 0, s[4:5]
	v_lshl_add_u64 v[36:37], v[18:19], 0, s[4:5]
	v_lshl_add_u64 v[38:39], v[20:21], 0, s[4:5]
	v_lshl_add_u64 v[40:41], v[22:23], 0, s[4:5]
	v_lshl_add_u64 v[42:43], v[24:25], 0, s[4:5]
	v_lshl_add_u64 v[44:45], v[26:27], 0, s[4:5]
	v_lshl_add_u64 v[70:71], v[28:29], 0, s[4:5]
	v_lshl_add_u64 v[72:73], v[30:31], 0, s[4:5]
	global_load_dword v110, v[34:35], off nt
	global_load_dword v111, v[36:37], off nt
	global_load_dword v112, v[38:39], off nt
	global_load_dword v113, v[40:41], off nt
	global_load_dword v114, v[42:43], off nt
	global_load_dword v115, v[44:45], off nt
	global_load_dword v116, v[70:71], off nt
	global_load_dword v117, v[72:73], off nt
	s_add_u32 s4, s4, 0x48000
	s_addc_u32 s5, s5, 0
	s_cmp_lg_u32 s4, 0x120000
	v_add_u32_e32 v41, 0x400, v2
	s_waitcnt vmcnt(30)
	ds_write2_b32 v2, v86, v87 offset1:66
	s_waitcnt vmcnt(28)
	ds_write2_b32 v2, v88, v89 offset0:132 offset1:198
	s_waitcnt vmcnt(26)
	ds_write2_b32 v41, v90, v91 offset0:8 offset1:74
	s_waitcnt vmcnt(24)
	ds_write2_b32 v41, v92, v93 offset0:140 offset1:206
	v_add_u32_e32 v2, 0x840, v2
	v_add_u32_e32 v41, 0x400, v2
	s_waitcnt vmcnt(22)
	ds_write2_b32 v2, v94, v95 offset1:66
	s_waitcnt vmcnt(20)
	ds_write2_b32 v2, v96, v97 offset0:132 offset1:198
	s_waitcnt vmcnt(18)
	ds_write2_b32 v41, v98, v99 offset0:8 offset1:74
	s_waitcnt vmcnt(16)
	ds_write2_b32 v41, v100, v101 offset0:140 offset1:206
	v_add_u32_e32 v2, 0x840, v2
	v_add_u32_e32 v41, 0x400, v2
	s_waitcnt vmcnt(14)
	ds_write2_b32 v2, v102, v103 offset1:66
	s_waitcnt vmcnt(12)
	ds_write2_b32 v2, v104, v105 offset0:132 offset1:198
	s_waitcnt vmcnt(10)
	ds_write2_b32 v41, v106, v107 offset0:8 offset1:74
	s_waitcnt vmcnt(8)
	ds_write2_b32 v41, v108, v109 offset0:140 offset1:206
	v_add_u32_e32 v2, 0x840, v2
	v_add_u32_e32 v41, 0x400, v2
	s_waitcnt vmcnt(6)
	ds_write2_b32 v2, v110, v111 offset1:66
	s_waitcnt vmcnt(4)
	ds_write2_b32 v2, v112, v113 offset0:132 offset1:198
	s_waitcnt vmcnt(2)
	ds_write2_b32 v41, v114, v115 offset0:8 offset1:74
	s_waitcnt vmcnt(0)
	ds_write2_b32 v41, v116, v117 offset0:140 offset1:206
	v_add_u32_e32 v2, 0x840, v2
	s_waitcnt lgkmcnt(0)
	ds_read2_b32 v[22:23], v46 offset1:8
	ds_read2_b32 v[26:27], v46 offset0:33 offset1:41
	ds_read2_b32 v[28:29], v46 offset0:66 offset1:74
	ds_read2_b32 v[30:31], v46 offset0:99 offset1:107
	ds_read2_b32 v[32:33], v46 offset0:132 offset1:140
	s_waitcnt lgkmcnt(4)
; #define LAS __attribute__((address_space(3)))
; __device__ __forceinline__ unsigned pk2(float lo, float hi) { return f2bf(lo) | (f2bf(hi) << 16); }
;     ...
;     const int c = lane & 7;
; #pragma unroll
;     for (int j = 0; j < 4; ++j) { const int n = (lane >> 3) + 8 * j; const LAS float* s = scr + (8 * c) * 33 + n;
;         u32x4v o; o.x = pk2(s[0 * 33], s[1 * 33]); o.y = pk2(s[2 * 33], s[3 * 33]); o.z = pk2(s[4 * 33], s[5 * 33]); o.w = pk2(s[6 * 33], s[7 * 33]);
;         *(u32x4v*)(WT + (size_t)(drow0 + dstride * n) * K + k0 + 8 * c) = o; }
; __global__ void __launch_bounds__(NTHR, 2) fwd_kernel(Args args) {
;     ...
;                 if (n0 < 1280) { const int hh = n0 >> 7, d0 = n0 & 127; transpose_item(w_in, DM, NIN, WIN, 64 * kb, n0, hh * 128 + (d0 & 64) + ((d0 & 63) >> 5), scr, lane, 2); }
	v_bfe_u32 v2, v22, 16, 1
	v_add3_u32 v2, v22, v2, s29
	s_waitcnt lgkmcnt(3)
	v_bfe_u32 v17, v26, 16, 1
	v_lshrrev_b32_e32 v2, 16, v2
	v_add3_u32 v17, v26, v17, s29
	ds_read2_b32 v[34:35], v46 offset0:165 offset1:173
	v_and_or_b32 v18, v17, s34, v2
	s_waitcnt lgkmcnt(3)
	v_bfe_u32 v2, v28, 16, 1
	v_add3_u32 v2, v28, v2, s29
	s_waitcnt lgkmcnt(2)
	v_bfe_u32 v17, v30, 16, 1
	ds_read2_b32 v[36:37], v46 offset0:198 offset1:206
	v_lshrrev_b32_e32 v2, 16, v2
	v_add3_u32 v17, v30, v17, s29
	ds_read2_b32 v[38:39], v46 offset0:231 offset1:239
	v_and_or_b32 v19, v17, s34, v2
	s_waitcnt lgkmcnt(3)
	v_bfe_u32 v2, v32, 16, 1
	v_add3_u32 v2, v32, v2, s29
	s_waitcnt lgkmcnt(2)
	v_bfe_u32 v17, v34, 16, 1
	v_lshrrev_b32_e32 v2, 16, v2
	v_add3_u32 v17, v34, v17, s29
	s_and_b32 s0, s7, 1
	s_and_b32 s4, s10, 0x7c0
	v_and_or_b32 v20, v17, s34, v2
	s_waitcnt lgkmcnt(1)
	v_bfe_u32 v2, v36, 16, 1
	s_or_b32 s4, s4, s0
	s_lshl_b32 s0, s6, 1
	v_add3_u32 v2, v36, v2, s29
	s_waitcnt lgkmcnt(0)
	v_bfe_u32 v17, v38, 16, 1
	v_lshl_add_u64 v[24:25], v[8:9], 0, s[0:1]
	v_lshrrev_b32_e32 v2, 16, v2
	v_add3_u32 v17, v38, v17, s29
	s_lshl_b32 s0, s4, 11
	v_and_or_b32 v21, v17, s34, v2
	v_or_b32_e32 v2, s0, v50
	v_lshlrev_b32_e32 v2, 1, v2
	v_lshl_add_u64 v[40:41], v[24:25], 0, v[2:3]
	v_bfe_u32 v2, v23, 16, 1
	v_add3_u32 v2, v23, v2, s29
	v_bfe_u32 v17, v27, 16, 1
	v_lshrrev_b32_e32 v2, 16, v2
	v_add3_u32 v17, v27, v17, s29
	global_store_dwordx4 v[40:41], v[18:21], off
	ds_read2_b32 v[22:23], v46 offset0:16 offset1:24
	s_mov_b64 s[4:5], 0
	v_and_or_b32 v18, v17, s34, v2
	v_bfe_u32 v2, v29, 16, 1
	v_add3_u32 v2, v29, v2, s29
	v_bfe_u32 v17, v31, 16, 1
	v_lshrrev_b32_e32 v2, 16, v2
	v_add3_u32 v17, v31, v17, s29
	v_and_or_b32 v19, v17, s34, v2
	v_bfe_u32 v2, v33, 16, 1
	v_add3_u32 v2, v33, v2, s29
	v_bfe_u32 v17, v35, 16, 1
	v_lshrrev_b32_e32 v2, 16, v2
	v_add3_u32 v17, v35, v17, s29
	v_and_or_b32 v20, v17, s34, v2
	v_bfe_u32 v2, v37, 16, 1
	v_add3_u32 v2, v37, v2, s29
	v_bfe_u32 v17, v39, 16, 1
	v_lshrrev_b32_e32 v2, 16, v2
	v_add3_u32 v17, v39, v17, s29
	v_and_or_b32 v21, v17, s34, v2
	v_or_b32_e32 v2, s0, v51
	v_lshlrev_b32_e32 v2, 1, v2
	v_lshl_add_u64 v[26:27], v[24:25], 0, v[2:3]
	global_store_dwordx4 v[26:27], v[18:21], off
	ds_read2_b32 v[26:27], v46 offset0:49 offset1:57
	ds_read2_b32 v[28:29], v46 offset0:82 offset1:90
	ds_read2_b32 v[30:31], v46 offset0:115 offset1:123
	s_waitcnt lgkmcnt(3)
	v_bfe_u32 v2, v22, 16, 1
	v_add3_u32 v2, v22, v2, s29
	s_waitcnt lgkmcnt(2)
	v_bfe_u32 v17, v26, 16, 1
	ds_read2_b32 v[32:33], v46 offset0:148 offset1:156
	v_lshrrev_b32_e32 v2, 16, v2
	v_add3_u32 v17, v26, v17, s29
	ds_read2_b32 v[34:35], v46 offset0:181 offset1:189
	v_and_or_b32 v18, v17, s34, v2
	s_waitcnt lgkmcnt(3)
	v_bfe_u32 v2, v28, 16, 1
	v_add3_u32 v2, v28, v2, s29
	s_waitcnt lgkmcnt(2)
	v_bfe_u32 v17, v30, 16, 1
	ds_read2_b32 v[36:37], v46 offset0:214 offset1:222
	v_lshrrev_b32_e32 v2, 16, v2
	v_add3_u32 v17, v30, v17, s29
	ds_read2_b32 v[38:39], v46 offset0:247 offset1:255
	v_and_or_b32 v19, v17, s34, v2
	s_waitcnt lgkmcnt(3)
	v_bfe_u32 v2, v32, 16, 1
	v_add3_u32 v2, v32, v2, s29
	s_waitcnt lgkmcnt(2)
	v_bfe_u32 v17, v34, 16, 1
	v_lshrrev_b32_e32 v2, 16, v2
	v_add3_u32 v17, v34, v17, s29
	v_and_or_b32 v20, v17, s34, v2
	s_waitcnt lgkmcnt(1)
	v_bfe_u32 v2, v36, 16, 1
	v_add3_u32 v2, v36, v2, s29
	s_waitcnt lgkmcnt(0)
	v_bfe_u32 v17, v38, 16, 1
	v_lshrrev_b32_e32 v2, 16, v2
	v_add3_u32 v17, v38, v17, s29
	v_and_or_b32 v21, v17, s34, v2
	v_or_b32_e32 v2, s0, v52
	v_lshlrev_b32_e32 v2, 1, v2
	v_lshl_add_u64 v[40:41], v[24:25], 0, v[2:3]
	v_bfe_u32 v2, v23, 16, 1
	v_add3_u32 v2, v23, v2, s29
	v_bfe_u32 v17, v27, 16, 1
	v_lshrrev_b32_e32 v2, 16, v2
	v_add3_u32 v17, v27, v17, s29
	global_store_dwordx4 v[40:41], v[18:21], off
	s_nop 1
	v_and_or_b32 v18, v17, s34, v2
	v_bfe_u32 v2, v29, 16, 1
	v_add3_u32 v2, v29, v2, s29
	v_bfe_u32 v17, v31, 16, 1
	v_lshrrev_b32_e32 v2, 16, v2
	v_add3_u32 v17, v31, v17, s29
	v_and_or_b32 v19, v17, s34, v2
	v_bfe_u32 v2, v33, 16, 1
	v_add3_u32 v2, v33, v2, s29
	v_bfe_u32 v17, v35, 16, 1
	v_lshrrev_b32_e32 v2, 16, v2
	v_add3_u32 v17, v35, v17, s29
	v_and_or_b32 v20, v17, s34, v2
	v_bfe_u32 v2, v37, 16, 1
	v_add3_u32 v2, v37, v2, s29
	v_bfe_u32 v17, v39, 16, 1
	v_lshrrev_b32_e32 v2, 16, v2
	v_add3_u32 v17, v39, v17, s29
	v_and_or_b32 v21, v17, s34, v2
	v_or_b32_e32 v2, s0, v53
	v_lshlrev_b32_e32 v2, 1, v2
	v_lshl_add_u64 v[22:23], v[24:25], 0, v[2:3]
	global_store_dwordx4 v[22:23], v[18:21], off
	s_waitcnt lgkmcnt(0)
	s_branch .LBB0_23

; #define LDS_WAIT() asm volatile("s_waitcnt lgkmcnt(0)" ::: "memory")
; #pragma unroll 8
;     for (int i = 0; i < 32; ++i) { const int kk = 2 * i + (lane >> 5); scr[kk * 33 + (lane & 31)] = __builtin_nontemporal_load(W + (size_t)(k0 + kk) * N + n0 + (lane & 31)); }
;     LDS_WAIT(); asm volatile("" ::: "memory");
; __global__ void __launch_bounds__(NTHR, 2) fwd_kernel(Args args) {
;     ...
;                 transpose_item(b ? ffn2_w2 : ffn1_w2, DFF, DM, b ? W2B : W2A, 64 * kb, 32 * nb, 32 * nb, scr, lane); continue; }
.LBB0_25:
	v_add_u32_e32 v20, s7, v2
	v_add_u32_e32 v22, 2, v20
	v_add_u32_e32 v24, 4, v20
	v_add_u32_e32 v26, 6, v20
	v_ashrrev_i32_e32 v21, 31, v20
	v_add_u32_e32 v28, 8, v20
	v_add_u32_e32 v30, 10, v20
	v_add_u32_e32 v32, 12, v20
	v_add_u32_e32 v34, 14, v20
	v_ashrrev_i32_e32 v23, 31, v22
	v_ashrrev_i32_e32 v25, 31, v24
	v_ashrrev_i32_e32 v27, 31, v26
	v_lshlrev_b64 v[20:21], 13, v[20:21]
	v_ashrrev_i32_e32 v29, 31, v28
	v_ashrrev_i32_e32 v31, 31, v30
	v_ashrrev_i32_e32 v33, 31, v32
	v_ashrrev_i32_e32 v35, 31, v34
	v_lshlrev_b64 v[22:23], 13, v[22:23]
	v_lshlrev_b64 v[24:25], 13, v[24:25]
	v_lshlrev_b64 v[26:27], 13, v[26:27]
	v_lshl_add_u64 v[20:21], v[18:19], 0, v[20:21]
	v_lshlrev_b64 v[28:29], 13, v[28:29]
	v_lshlrev_b64 v[30:31], 13, v[30:31]
	v_lshlrev_b64 v[32:33], 13, v[32:33]
	v_lshlrev_b64 v[34:35], 13, v[34:35]
	v_lshl_add_u64 v[22:23], v[18:19], 0, v[22:23]
	v_lshl_add_u64 v[24:25], v[18:19], 0, v[24:25]
	v_lshl_add_u64 v[26:27], v[18:19], 0, v[26:27]
	v_lshl_add_u64 v[28:29], v[18:19], 0, v[28:29]
	v_lshl_add_u64 v[30:31], v[18:19], 0, v[30:31]
	v_lshl_add_u64 v[32:33], v[18:19], 0, v[32:33]
	v_lshl_add_u64 v[34:35], v[18:19], 0, v[34:35]
	global_load_dword v86, v[20:21], off nt
	global_load_dword v87, v[22:23], off nt
	global_load_dword v88, v[24:25], off nt
	global_load_dword v89, v[26:27], off nt
	global_load_dword v90, v[28:29], off nt
	global_load_dword v91, v[30:31], off nt
	global_load_dword v92, v[32:33], off nt
	global_load_dword v93, v[34:35], off nt
	s_add_i32 s7, s7, 16
	s_cmp_lg_u32 s7, 64
	v_add_u32_e32 v20, s7, v2
	v_add_u32_e32 v22, 2, v20
	v_add_u32_e32 v24, 4, v20
	v_add_u32_e32 v26, 6, v20
	v_ashrrev_i32_e32 v21, 31, v20
	v_add_u32_e32 v28, 8, v20
	v_add_u32_e32 v30, 10, v20
	v_add_u32_e32 v32, 12, v20
	v_add_u32_e32 v34, 14, v20
	v_ashrrev_i32_e32 v23, 31, v22
	v_ashrrev_i32_e32 v25, 31, v24
	v_ashrrev_i32_e32 v27, 31, v26
	v_lshlrev_b64 v[20:21], 13, v[20:21]
	v_ashrrev_i32_e32 v29, 31, v28
	v_ashrrev_i32_e32 v31, 31, v30
	v_ashrrev_i32_e32 v33, 31, v32
	v_ashrrev_i32_e32 v35, 31, v34
	v_lshlrev_b64 v[22:23], 13, v[22:23]
	v_lshlrev_b64 v[24:25], 13, v[24:25]
	v_lshlrev_b64 v[26:27], 13, v[26:27]
	v_lshl_add_u64 v[20:21], v[18:19], 0, v[20:21]
	v_lshlrev_b64 v[28:29], 13, v[28:29]
	v_lshlrev_b64 v[30:31], 13, v[30:31]
	v_lshlrev_b64 v[32:33], 13, v[32:33]
	v_lshlrev_b64 v[34:35], 13, v[34:35]
	v_lshl_add_u64 v[22:23], v[18:19], 0, v[22:23]
	v_lshl_add_u64 v[24:25], v[18:19], 0, v[24:25]
	v_lshl_add_u64 v[26:27], v[18:19], 0, v[26:27]
	v_lshl_add_u64 v[28:29], v[18:19], 0, v[28:29]
	v_lshl_add_u64 v[30:31], v[18:19], 0, v[30:31]
	v_lshl_add_u64 v[32:33], v[18:19], 0, v[32:33]
	v_lshl_add_u64 v[34:35], v[18:19], 0, v[34:35]
	global_load_dword v94, v[20:21], off nt
	global_load_dword v95, v[22:23], off nt
	global_load_dword v96, v[24:25], off nt
	global_load_dword v97, v[26:27], off nt
	global_load_dword v98, v[28:29], off nt
	global_load_dword v99, v[30:31], off nt
	global_load_dword v100, v[32:33], off nt
	global_load_dword v101, v[34:35], off nt
	s_add_i32 s7, s7, 16
	s_cmp_lg_u32 s7, 64
	v_add_u32_e32 v20, s7, v2
	v_add_u32_e32 v22, 2, v20
	v_add_u32_e32 v24, 4, v20
	v_add_u32_e32 v26, 6, v20
	v_ashrrev_i32_e32 v21, 31, v20
	v_add_u32_e32 v28, 8, v20
	v_add_u32_e32 v30, 10, v20
	v_add_u32_e32 v32, 12, v20
	v_add_u32_e32 v34, 14, v20
	v_ashrrev_i32_e32 v23, 31, v22
	v_ashrrev_i32_e32 v25, 31, v24
	v_ashrrev_i32_e32 v27, 31, v26
	v_lshlrev_b64 v[20:21], 13, v[20:21]
	v_ashrrev_i32_e32 v29, 31, v28
	v_ashrrev_i32_e32 v31, 31, v30
	v_ashrrev_i32_e32 v33, 31, v32
	v_ashrrev_i32_e32 v35, 31, v34
	v_lshlrev_b64 v[22:23], 13, v[22:23]
	v_lshlrev_b64 v[24:25], 13, v[24:25]
	v_lshlrev_b64 v[26:27], 13, v[26:27]
	v_lshl_add_u64 v[20:21], v[18:19], 0, v[20:21]
	v_lshlrev_b64 v[28:29], 13, v[28:29]
	v_lshlrev_b64 v[30:31], 13, v[30:31]
	v_lshlrev_b64 v[32:33], 13, v[32:33]
	v_lshlrev_b64 v[34:35], 13, v[34:35]
	v_lshl_add_u64 v[22:23], v[18:19], 0, v[22:23]
	v_lshl_add_u64 v[24:25], v[18:19], 0, v[24:25]
	v_lshl_add_u64 v[26:27], v[18:19], 0, v[26:27]
	v_lshl_add_u64 v[28:29], v[18:19], 0, v[28:29]
	v_lshl_add_u64 v[30:31], v[18:19], 0, v[30:31]
	v_lshl_add_u64 v[32:33], v[18:19], 0, v[32:33]
	v_lshl_add_u64 v[34:35], v[18:19], 0, v[34:35]
	global_load_dword v102, v[20:21], off nt
	global_load_dword v103, v[22:23], off nt
	global_load_dword v104, v[24:25], off nt
	global_load_dword v105, v[26:27], off nt
	global_load_dword v106, v[28:29], off nt
	global_load_dword v107, v[30:31], off nt
	global_load_dword v108, v[32:33], off nt
	global_load_dword v109, v[34:35], off nt
	s_add_i32 s7, s7, 16
	s_cmp_lg_u32 s7, 64
	v_add_u32_e32 v20, s7, v2
	v_add_u32_e32 v22, 2, v20
	v_add_u32_e32 v24, 4, v20
	v_add_u32_e32 v26, 6, v20
	v_ashrrev_i32_e32 v21, 31, v20
	v_add_u32_e32 v28, 8, v20
	v_add_u32_e32 v30, 10, v20
	v_add_u32_e32 v32, 12, v20
	v_add_u32_e32 v34, 14, v20
	v_ashrrev_i32_e32 v23, 31, v22
	v_ashrrev_i32_e32 v25, 31, v24
	v_ashrrev_i32_e32 v27, 31, v26
	v_lshlrev_b64 v[20:21], 13, v[20:21]
	v_ashrrev_i32_e32 v29, 31, v28
	v_ashrrev_i32_e32 v31, 31, v30
	v_ashrrev_i32_e32 v33, 31, v32
	v_ashrrev_i32_e32 v35, 31, v34
	v_lshlrev_b64 v[22:23], 13, v[22:23]
	v_lshlrev_b64 v[24:25], 13, v[24:25]
	v_lshlrev_b64 v[26:27], 13, v[26:27]
	v_lshl_add_u64 v[20:21], v[18:19], 0, v[20:21]
	v_lshlrev_b64 v[28:29], 13, v[28:29]
	v_lshlrev_b64 v[30:31], 13, v[30:31]
	v_lshlrev_b64 v[32:33], 13, v[32:33]
	v_lshlrev_b64 v[34:35], 13, v[34:35]
	v_lshl_add_u64 v[22:23], v[18:19], 0, v[22:23]
	v_lshl_add_u64 v[24:25], v[18:19], 0, v[24:25]
	v_lshl_add_u64 v[26:27], v[18:19], 0, v[26:27]
	v_lshl_add_u64 v[28:29], v[18:19], 0, v[28:29]
	v_lshl_add_u64 v[30:31], v[18:19], 0, v[30:31]
	v_lshl_add_u64 v[32:33], v[18:19], 0, v[32:33]
	v_lshl_add_u64 v[34:35], v[18:19], 0, v[34:35]
	global_load_dword v110, v[20:21], off nt
	global_load_dword v111, v[22:23], off nt
	global_load_dword v112, v[24:25], off nt
	global_load_dword v113, v[26:27], off nt
	global_load_dword v114, v[28:29], off nt
	global_load_dword v115, v[30:31], off nt
	global_load_dword v116, v[32:33], off nt
	global_load_dword v117, v[34:35], off nt
	s_add_i32 s7, s7, 16
	s_cmp_lg_u32 s7, 64
	v_add_u32_e32 v28, 0x400, v17
	s_waitcnt vmcnt(30)
; #define LAS __attribute__((address_space(3)))
; __device__ __forceinline__ unsigned pk2(float lo, float hi) { return f2bf(lo) | (f2bf(hi) << 16); }
; #define LDS_WAIT() asm volatile("s_waitcnt lgkmcnt(0)" ::: "memory")
;     ...
;     LDS_WAIT(); asm volatile("" ::: "memory");
;     const int c = lane & 7;
; #pragma unroll
;     for (int j = 0; j < 4; ++j) { const int n = (lane >> 3) + 8 * j; const LAS float* s = scr + (8 * c) * 33 + n;
;         u32x4v o; o.x = pk2(s[0 * 33], s[1 * 33]); o.y = pk2(s[2 * 33], s[3 * 33]); o.z = pk2(s[4 * 33], s[5 * 33]); o.w = pk2(s[6 * 33], s[7 * 33]);
;         *(u32x4v*)(WT + (size_t)(drow0 + dstride * n) * K + k0 + 8 * c) = o; }
;     LDS_WAIT(); asm volatile("" ::: "memory");
; __global__ void __launch_bounds__(NTHR, 2) fwd_kernel(Args args) {
;     ...
;                 transpose_item(b ? ffn2_w2 : ffn1_w2, DFF, DM, b ? W2B : W2A, 64 * kb, 32 * nb, 32 * nb, scr, lane); continue; }
	ds_write2_b32 v17, v86, v87 offset1:66
	s_waitcnt vmcnt(28)
	ds_write2_b32 v17, v88, v89 offset0:132 offset1:198
	s_waitcnt vmcnt(26)
	ds_write2_b32 v28, v90, v91 offset0:8 offset1:74
	s_waitcnt vmcnt(24)
	ds_write2_b32 v28, v92, v93 offset0:140 offset1:206
	v_add_u32_e32 v17, 0x840, v17
	v_add_u32_e32 v28, 0x400, v17
	s_waitcnt vmcnt(22)
	ds_write2_b32 v17, v94, v95 offset1:66
	s_waitcnt vmcnt(20)
	ds_write2_b32 v17, v96, v97 offset0:132 offset1:198
	s_waitcnt vmcnt(18)
	ds_write2_b32 v28, v98, v99 offset0:8 offset1:74
	s_waitcnt vmcnt(16)
	ds_write2_b32 v28, v100, v101 offset0:140 offset1:206
	v_add_u32_e32 v17, 0x840, v17
	v_add_u32_e32 v28, 0x400, v17
	s_waitcnt vmcnt(14)
	ds_write2_b32 v17, v102, v103 offset1:66
	s_waitcnt vmcnt(12)
	ds_write2_b32 v17, v104, v105 offset0:132 offset1:198
	s_waitcnt vmcnt(10)
	ds_write2_b32 v28, v106, v107 offset0:8 offset1:74
	s_waitcnt vmcnt(8)
	ds_write2_b32 v28, v108, v109 offset0:140 offset1:206
	v_add_u32_e32 v17, 0x840, v17
	v_add_u32_e32 v28, 0x400, v17
	s_waitcnt vmcnt(6)
	ds_write2_b32 v17, v110, v111 offset1:66
	s_waitcnt vmcnt(4)
	ds_write2_b32 v17, v112, v113 offset0:132 offset1:198
	s_waitcnt vmcnt(2)
	ds_write2_b32 v28, v114, v115 offset0:8 offset1:74
	s_waitcnt vmcnt(0)
	ds_write2_b32 v28, v116, v117 offset0:140 offset1:206
	v_add_u32_e32 v17, 0x840, v17
	s_waitcnt lgkmcnt(0)
	s_and_b64 s[4:5], s[4:5], exec
	v_readlane_b32 s4, v255, 9
	ds_read2_b32 v[22:23], v46 offset1:8
	s_cselect_b32 s10, s4, s28
	s_cselect_b32 s11, s86, s3
	s_ashr_i32 s7, s6, 31
	ds_read2_b32 v[26:27], v46 offset0:33 offset1:41
	s_lshl_b64 s[4:5], s[6:7], 1
	s_add_u32 s4, s11, s4
	ds_read2_b32 v[28:29], v46 offset0:66 offset1:74
	s_addc_u32 s5, s10, s5
	v_lshlrev_b32_e32 v2, 1, v4
	ds_read2_b32 v[30:31], v46 offset0:99 offset1:107
	v_lshl_add_u64 v[24:25], s[4:5], 0, v[2:3]
	s_waitcnt lgkmcnt(3)
	v_bfe_u32 v2, v22, 16, 1
	v_add3_u32 v2, v22, v2, s29
	s_waitcnt lgkmcnt(2)
	v_bfe_u32 v17, v26, 16, 1
	ds_read2_b32 v[32:33], v46 offset0:132 offset1:140
	v_lshrrev_b32_e32 v2, 16, v2
	v_add3_u32 v17, v26, v17, s29
	ds_read2_b32 v[34:35], v46 offset0:165 offset1:173
	v_and_or_b32 v18, v17, s34, v2
	s_waitcnt lgkmcnt(3)
	v_bfe_u32 v2, v28, 16, 1
	v_add3_u32 v2, v28, v2, s29
	s_waitcnt lgkmcnt(2)
	v_bfe_u32 v17, v30, 16, 1
	ds_read2_b32 v[36:37], v46 offset0:198 offset1:206
	v_lshrrev_b32_e32 v2, 16, v2
	v_add3_u32 v17, v30, v17, s29
	ds_read2_b32 v[38:39], v46 offset0:231 offset1:239
	v_and_or_b32 v19, v17, s34, v2
	s_waitcnt lgkmcnt(3)
	v_bfe_u32 v2, v32, 16, 1
	v_add3_u32 v2, v32, v2, s29
	s_waitcnt lgkmcnt(2)
	v_bfe_u32 v17, v34, 16, 1
	v_lshrrev_b32_e32 v2, 16, v2
	v_add3_u32 v17, v34, v17, s29
	v_and_or_b32 v20, v17, s34, v2
	s_waitcnt lgkmcnt(1)
	v_bfe_u32 v2, v36, 16, 1
	v_add3_u32 v2, v36, v2, s29
	s_waitcnt lgkmcnt(0)
	v_bfe_u32 v17, v38, 16, 1
	v_lshrrev_b32_e32 v2, 16, v2
	v_add3_u32 v17, v38, v17, s29
	v_and_or_b32 v21, v17, s34, v2
	v_or_b32_e32 v2, s0, v5
	v_mul_u32_u24_e32 v2, 0x1600, v2
	v_lshlrev_b32_e32 v2, 1, v2
	v_lshl_add_u64 v[40:41], v[24:25], 0, v[2:3]
	v_bfe_u32 v2, v23, 16, 1
	v_add3_u32 v2, v23, v2, s29
	v_bfe_u32 v17, v27, 16, 1
	v_lshrrev_b32_e32 v2, 16, v2
	v_add3_u32 v17, v27, v17, s29
	global_store_dwordx4 v[40:41], v[18:21], off
	ds_read2_b32 v[22:23], v46 offset0:16 offset1:24
	s_nop 0
	v_and_or_b32 v18, v17, s34, v2
	v_bfe_u32 v2, v29, 16, 1
	v_add3_u32 v2, v29, v2, s29
	v_bfe_u32 v17, v31, 16, 1
	v_lshrrev_b32_e32 v2, 16, v2
	v_add3_u32 v17, v31, v17, s29
	v_and_or_b32 v19, v17, s34, v2
	v_bfe_u32 v2, v33, 16, 1
	v_add3_u32 v2, v33, v2, s29
	v_bfe_u32 v17, v35, 16, 1
	v_lshrrev_b32_e32 v2, 16, v2
	v_add3_u32 v17, v35, v17, s29
	v_and_or_b32 v20, v17, s34, v2
	v_bfe_u32 v2, v37, 16, 1
	v_add3_u32 v2, v37, v2, s29
	v_bfe_u32 v17, v39, 16, 1
	v_lshrrev_b32_e32 v2, 16, v2
	v_add3_u32 v17, v39, v17, s29
	v_and_or_b32 v21, v17, s34, v2
	v_or_b32_e32 v2, s0, v47
	v_mul_u32_u24_e32 v2, 0x1600, v2
	v_lshlrev_b32_e32 v2, 1, v2
	v_lshl_add_u64 v[26:27], v[24:25], 0, v[2:3]
	global_store_dwordx4 v[26:27], v[18:21], off
	ds_read2_b32 v[26:27], v46 offset0:49 offset1:57
	ds_read2_b32 v[28:29], v46 offset0:82 offset1:90
	ds_read2_b32 v[30:31], v46 offset0:115 offset1:123
	s_waitcnt lgkmcnt(3)
	v_bfe_u32 v2, v22, 16, 1
	v_add3_u32 v2, v22, v2, s29
	s_waitcnt lgkmcnt(2)
	v_bfe_u32 v17, v26, 16, 1
	ds_read2_b32 v[32:33], v46 offset0:148 offset1:156
	v_lshrrev_b32_e32 v2, 16, v2
	v_add3_u32 v17, v26, v17, s29
	ds_read2_b32 v[34:35], v46 offset0:181 offset1:189
	v_and_or_b32 v18, v17, s34, v2
	s_waitcnt lgkmcnt(3)
	v_bfe_u32 v2, v28, 16, 1
	v_add3_u32 v2, v28, v2, s29
	s_waitcnt lgkmcnt(2)
	v_bfe_u32 v17, v30, 16, 1
	ds_read2_b32 v[36:37], v46 offset0:214 offset1:222
	v_lshrrev_b32_e32 v2, 16, v2
	v_add3_u32 v17, v30, v17, s29
	ds_read2_b32 v[38:39], v46 offset0:247 offset1:255
	v_and_or_b32 v19, v17, s34, v2
	s_waitcnt lgkmcnt(3)
	v_bfe_u32 v2, v32, 16, 1
	v_add3_u32 v2, v32, v2, s29
	s_waitcnt lgkmcnt(2)
	v_bfe_u32 v17, v34, 16, 1
	v_lshrrev_b32_e32 v2, 16, v2
	v_add3_u32 v17, v34, v17, s29
	v_and_or_b32 v20, v17, s34, v2
	s_waitcnt lgkmcnt(1)
	v_bfe_u32 v2, v36, 16, 1
	v_add3_u32 v2, v36, v2, s29
	s_waitcnt lgkmcnt(0)
	v_bfe_u32 v17, v38, 16, 1
	v_lshrrev_b32_e32 v2, 16, v2
	v_add3_u32 v17, v38, v17, s29
	v_and_or_b32 v21, v17, s34, v2
	v_or_b32_e32 v2, s0, v48
	v_mul_u32_u24_e32 v2, 0x1600, v2
	v_lshlrev_b32_e32 v2, 1, v2
	v_lshl_add_u64 v[40:41], v[24:25], 0, v[2:3]
	v_bfe_u32 v2, v23, 16, 1
	v_add3_u32 v2, v23, v2, s29
	v_bfe_u32 v17, v27, 16, 1
	v_lshrrev_b32_e32 v2, 16, v2
	v_add3_u32 v17, v27, v17, s29
	global_store_dwordx4 v[40:41], v[18:21], off
	s_nop 1
	v_and_or_b32 v18, v17, s34, v2
	v_bfe_u32 v2, v29, 16, 1
	v_add3_u32 v2, v29, v2, s29
	v_bfe_u32 v17, v31, 16, 1
	v_lshrrev_b32_e32 v2, 16, v2
	v_add3_u32 v17, v31, v17, s29
	v_and_or_b32 v19, v17, s34, v2
	v_bfe_u32 v2, v33, 16, 1
	v_add3_u32 v2, v33, v2, s29
	v_bfe_u32 v17, v35, 16, 1
	v_lshrrev_b32_e32 v2, 16, v2
	v_add3_u32 v17, v35, v17, s29
	v_and_or_b32 v20, v17, s34, v2
	v_bfe_u32 v2, v37, 16, 1
	v_add3_u32 v2, v37, v2, s29
	v_bfe_u32 v17, v39, 16, 1
	v_lshrrev_b32_e32 v2, 16, v2
	v_add3_u32 v17, v39, v17, s29
	v_and_or_b32 v21, v17, s34, v2
	v_or_b32_e32 v2, s0, v49
	v_mul_u32_u24_e32 v2, 0x1600, v2
	v_lshlrev_b32_e32 v2, 1, v2
	v_lshl_add_u64 v[22:23], v[24:25], 0, v[2:3]
	global_store_dwordx4 v[22:23], v[18:21], off
	s_waitcnt lgkmcnt(0)

; #define LDS_WAIT() asm volatile("s_waitcnt lgkmcnt(0)" ::: "memory")
; #pragma unroll 8
;     for (int i = 0; i < 32; ++i) { const int kk = 2 * i + (lane >> 5); scr[kk * 33 + (lane & 31)] = __builtin_nontemporal_load(W + (size_t)(k0 + kk) * N + n0 + (lane & 31)); }
;     LDS_WAIT(); asm volatile("" ::: "memory");
; __global__ void __launch_bounds__(NTHR, 2) fwd_kernel(Args args) {
;     ...
;                 transpose_item(b ? ffn2_w13 : ffn1_w13, DM, 2 * DFF, b ? W13B : W13A, 64 * kb, 32 * nb, swiglu_row(32 * nb), scr, lane); continue; }
.LBB0_33:
	v_lshl_add_u64 v[34:35], v[32:33], 0, s[10:11]
	v_lshl_add_u64 v[36:37], v[30:31], 0, s[10:11]
	v_lshl_add_u64 v[38:39], v[28:29], 0, s[10:11]
	v_lshl_add_u64 v[40:41], v[26:27], 0, s[10:11]
	v_lshl_add_u64 v[42:43], v[24:25], 0, s[10:11]
	v_lshl_add_u64 v[44:45], v[22:23], 0, s[10:11]
	v_lshl_add_u64 v[70:71], v[20:21], 0, s[10:11]
	v_lshl_add_u64 v[72:73], v[18:19], 0, s[10:11]
	global_load_dword v86, v[34:35], off nt
	global_load_dword v87, v[36:37], off nt
	global_load_dword v88, v[38:39], off nt
	global_load_dword v89, v[40:41], off nt
	global_load_dword v90, v[42:43], off nt
	global_load_dword v91, v[44:45], off nt
	global_load_dword v92, v[70:71], off nt
	global_load_dword v93, v[72:73], off nt
	s_add_u32 s10, s10, 0xb0000
	s_addc_u32 s11, s11, 0
	s_cmp_lg_u32 s10, 0x2c0000
	v_lshl_add_u64 v[34:35], v[32:33], 0, s[10:11]
	v_lshl_add_u64 v[36:37], v[30:31], 0, s[10:11]
	v_lshl_add_u64 v[38:39], v[28:29], 0, s[10:11]
	v_lshl_add_u64 v[40:41], v[26:27], 0, s[10:11]
	v_lshl_add_u64 v[42:43], v[24:25], 0, s[10:11]
	v_lshl_add_u64 v[44:45], v[22:23], 0, s[10:11]
	v_lshl_add_u64 v[70:71], v[20:21], 0, s[10:11]
	v_lshl_add_u64 v[72:73], v[18:19], 0, s[10:11]
	global_load_dword v94, v[34:35], off nt
	global_load_dword v95, v[36:37], off nt
	global_load_dword v96, v[38:39], off nt
	global_load_dword v97, v[40:41], off nt
	global_load_dword v98, v[42:43], off nt
	global_load_dword v99, v[44:45], off nt
	global_load_dword v100, v[70:71], off nt
	global_load_dword v101, v[72:73], off nt
	s_add_u32 s10, s10, 0xb0000
	s_addc_u32 s11, s11, 0
	s_cmp_lg_u32 s10, 0x2c0000
	v_lshl_add_u64 v[34:35], v[32:33], 0, s[10:11]
	v_lshl_add_u64 v[36:37], v[30:31], 0, s[10:11]
	v_lshl_add_u64 v[38:39], v[28:29], 0, s[10:11]
	v_lshl_add_u64 v[40:41], v[26:27], 0, s[10:11]
	v_lshl_add_u64 v[42:43], v[24:25], 0, s[10:11]
	v_lshl_add_u64 v[44:45], v[22:23], 0, s[10:11]
	v_lshl_add_u64 v[70:71], v[20:21], 0, s[10:11]
	v_lshl_add_u64 v[72:73], v[18:19], 0, s[10:11]
	global_load_dword v102, v[34:35], off nt
	global_load_dword v103, v[36:37], off nt
	global_load_dword v104, v[38:39], off nt
	global_load_dword v105, v[40:41], off nt
	global_load_dword v106, v[42:43], off nt
	global_load_dword v107, v[44:45], off nt
	global_load_dword v108, v[70:71], off nt
	global_load_dword v109, v[72:73], off nt
	s_add_u32 s10, s10, 0xb0000
	s_addc_u32 s11, s11, 0
	s_cmp_lg_u32 s10, 0x2c0000
	v_lshl_add_u64 v[34:35], v[32:33], 0, s[10:11]
	v_lshl_add_u64 v[36:37], v[30:31], 0, s[10:11]
	v_lshl_add_u64 v[38:39], v[28:29], 0, s[10:11]
	v_lshl_add_u64 v[40:41], v[26:27], 0, s[10:11]
	v_lshl_add_u64 v[42:43], v[24:25], 0, s[10:11]
	v_lshl_add_u64 v[44:45], v[22:23], 0, s[10:11]
	v_lshl_add_u64 v[70:71], v[20:21], 0, s[10:11]
	v_lshl_add_u64 v[72:73], v[18:19], 0, s[10:11]
	global_load_dword v110, v[34:35], off nt
	global_load_dword v111, v[36:37], off nt
	global_load_dword v112, v[38:39], off nt
	global_load_dword v113, v[40:41], off nt
	global_load_dword v114, v[42:43], off nt
	global_load_dword v115, v[44:45], off nt
	global_load_dword v116, v[70:71], off nt
	global_load_dword v117, v[72:73], off nt
	s_add_u32 s10, s10, 0xb0000
	s_addc_u32 s11, s11, 0
	s_cmp_lg_u32 s10, 0x2c0000
	v_add_u32_e32 v41, 0x400, v2
	s_waitcnt vmcnt(30)
	ds_write2_b32 v2, v86, v87 offset1:66
	s_waitcnt vmcnt(28)
	ds_write2_b32 v2, v88, v89 offset0:132 offset1:198
	s_waitcnt vmcnt(26)
	ds_write2_b32 v41, v90, v91 offset0:8 offset1:74
	s_waitcnt vmcnt(24)
	ds_write2_b32 v41, v92, v93 offset0:140 offset1:206
	v_add_u32_e32 v2, 0x840, v2
	v_add_u32_e32 v41, 0x400, v2
	s_waitcnt vmcnt(22)
	ds_write2_b32 v2, v94, v95 offset1:66
	s_waitcnt vmcnt(20)
	ds_write2_b32 v2, v96, v97 offset0:132 offset1:198
	s_waitcnt vmcnt(18)
	ds_write2_b32 v41, v98, v99 offset0:8 offset1:74
	s_waitcnt vmcnt(16)
	ds_write2_b32 v41, v100, v101 offset0:140 offset1:206
	v_add_u32_e32 v2, 0x840, v2
	v_add_u32_e32 v41, 0x400, v2
	s_waitcnt vmcnt(14)
	ds_write2_b32 v2, v102, v103 offset1:66
	s_waitcnt vmcnt(12)
	ds_write2_b32 v2, v104, v105 offset0:132 offset1:198
	s_waitcnt vmcnt(10)
	ds_write2_b32 v41, v106, v107 offset0:8 offset1:74
	s_waitcnt vmcnt(8)
	ds_write2_b32 v41, v108, v109 offset0:140 offset1:206
	v_add_u32_e32 v2, 0x840, v2
	v_add_u32_e32 v41, 0x400, v2
	s_waitcnt vmcnt(6)
	ds_write2_b32 v2, v110, v111 offset1:66
	s_waitcnt vmcnt(4)
	ds_write2_b32 v2, v112, v113 offset0:132 offset1:198
	s_waitcnt vmcnt(2)
	ds_write2_b32 v41, v114, v115 offset0:8 offset1:74
	s_waitcnt vmcnt(0)
	ds_write2_b32 v41, v116, v117 offset0:140 offset1:206
	v_add_u32_e32 v2, 0x840, v2
	s_and_b64 s[4:5], s[4:5], exec
	s_waitcnt lgkmcnt(0)
; #define LAS __attribute__((address_space(3)))
; __device__ __forceinline__ unsigned pk2(float lo, float hi) { return f2bf(lo) | (f2bf(hi) << 16); }
;     ...
;     const int c = lane & 7;
; #pragma unroll
;     for (int j = 0; j < 4; ++j) { const int n = (lane >> 3) + 8 * j; const LAS float* s = scr + (8 * c) * 33 + n;
;         u32x4v o; o.x = pk2(s[0 * 33], s[1 * 33]); o.y = pk2(s[2 * 33], s[3 * 33]); o.z = pk2(s[4 * 33], s[5 * 33]); o.w = pk2(s[6 * 33], s[7 * 33]);
;         *(u32x4v*)(WT + (size_t)(drow0 + dstride * n) * K + k0 + 8 * c) = o; }
; __global__ void __launch_bounds__(NTHR, 2) fwd_kernel(Args args) {
;     ...
;                 transpose_item(b ? ffn2_w13 : ffn1_w13, DM, 2 * DFF, b ? W13B : W13A, 64 * kb, 32 * nb, swiglu_row(32 * nb), scr, lane); continue; }
	v_readlane_b32 s4, v255, 8
	v_readlane_b32 s5, v255, 4
	s_cselect_b32 s10, s4, s5
	v_readlane_b32 s4, v255, 7
	v_readlane_b32 s5, v255, 3
	ds_read2_b32 v[22:23], v46 offset1:8
	s_cselect_b32 s11, s4, s5
	s_ashr_i32 s7, s6, 31
	ds_read2_b32 v[26:27], v46 offset0:33 offset1:41
	s_lshl_b64 s[4:5], s[6:7], 1
	s_add_u32 s4, s11, s4
	ds_read2_b32 v[28:29], v46 offset0:66 offset1:74
	s_addc_u32 s5, s10, s5
	v_lshlrev_b32_e32 v2, 1, v4
	ds_read2_b32 v[30:31], v46 offset0:99 offset1:107
	v_lshl_add_u64 v[24:25], s[4:5], 0, v[2:3]
	s_waitcnt lgkmcnt(3)
	v_bfe_u32 v2, v22, 16, 1
	v_add3_u32 v2, v22, v2, s29
	s_waitcnt lgkmcnt(2)
	v_bfe_u32 v17, v26, 16, 1
	ds_read2_b32 v[32:33], v46 offset0:132 offset1:140
	v_lshrrev_b32_e32 v2, 16, v2
	v_add3_u32 v17, v26, v17, s29
	ds_read2_b32 v[34:35], v46 offset0:165 offset1:173
	v_and_or_b32 v18, v17, s34, v2
	s_waitcnt lgkmcnt(3)
	v_bfe_u32 v2, v28, 16, 1
	v_add3_u32 v2, v28, v2, s29
	s_waitcnt lgkmcnt(2)
	v_bfe_u32 v17, v30, 16, 1
	ds_read2_b32 v[36:37], v46 offset0:198 offset1:206
	v_lshrrev_b32_e32 v2, 16, v2
	v_add3_u32 v17, v30, v17, s29
	ds_read2_b32 v[38:39], v46 offset0:231 offset1:239
	v_and_or_b32 v19, v17, s34, v2
	s_waitcnt lgkmcnt(3)
	v_bfe_u32 v2, v32, 16, 1
	v_add3_u32 v2, v32, v2, s29
	s_waitcnt lgkmcnt(2)
	v_bfe_u32 v17, v34, 16, 1
	v_lshrrev_b32_e32 v2, 16, v2
	v_add3_u32 v17, v34, v17, s29
	v_and_or_b32 v20, v17, s34, v2
	s_waitcnt lgkmcnt(1)
	v_bfe_u32 v2, v36, 16, 1
	v_add3_u32 v2, v36, v2, s29
	s_waitcnt lgkmcnt(0)
	v_bfe_u32 v17, v38, 16, 1
	v_lshrrev_b32_e32 v2, 16, v2
	v_add3_u32 v17, v38, v17, s29
	v_add_u32_e32 v40, s0, v5
	v_and_or_b32 v21, v17, s34, v2
	v_ashrrev_i32_e32 v41, 31, v40
	v_bfe_u32 v2, v23, 16, 1
	v_lshlrev_b64 v[40:41], 12, v[40:41]
	v_add3_u32 v2, v23, v2, s29
	v_bfe_u32 v17, v27, 16, 1
	v_lshl_add_u64 v[40:41], v[24:25], 0, v[40:41]
	v_lshrrev_b32_e32 v2, 16, v2
	v_add3_u32 v17, v27, v17, s29
	global_store_dwordx4 v[40:41], v[18:21], off
	v_add_u32_e32 v22, s0, v47
	v_ashrrev_i32_e32 v23, 31, v22
	v_and_or_b32 v18, v17, s34, v2
	v_bfe_u32 v2, v29, 16, 1
	v_add3_u32 v2, v29, v2, s29
	v_bfe_u32 v17, v31, 16, 1
	v_lshrrev_b32_e32 v2, 16, v2
	v_add3_u32 v17, v31, v17, s29
	v_and_or_b32 v19, v17, s34, v2
	v_bfe_u32 v2, v33, 16, 1
	v_add3_u32 v2, v33, v2, s29
	v_bfe_u32 v17, v35, 16, 1
	v_lshrrev_b32_e32 v2, 16, v2
	v_add3_u32 v17, v35, v17, s29
	v_and_or_b32 v20, v17, s34, v2
	v_bfe_u32 v2, v37, 16, 1
	v_add3_u32 v2, v37, v2, s29
	v_bfe_u32 v17, v39, 16, 1
	v_lshrrev_b32_e32 v2, 16, v2
	v_add3_u32 v17, v39, v17, s29
	v_lshlrev_b64 v[22:23], 12, v[22:23]
	v_and_or_b32 v21, v17, s34, v2
	ds_read2_b32 v[26:27], v46 offset0:16 offset1:24
	v_lshl_add_u64 v[22:23], v[24:25], 0, v[22:23]
	global_store_dwordx4 v[22:23], v[18:21], off
	ds_read2_b32 v[22:23], v46 offset0:49 offset1:57
	ds_read2_b32 v[28:29], v46 offset0:82 offset1:90
	ds_read2_b32 v[30:31], v46 offset0:115 offset1:123
	s_waitcnt lgkmcnt(3)
	v_bfe_u32 v2, v26, 16, 1
	v_add3_u32 v2, v26, v2, s29
	s_waitcnt lgkmcnt(2)
	v_bfe_u32 v17, v22, 16, 1
	ds_read2_b32 v[32:33], v46 offset0:148 offset1:156
	v_lshrrev_b32_e32 v2, 16, v2
	v_add3_u32 v17, v22, v17, s29
	ds_read2_b32 v[34:35], v46 offset0:181 offset1:189
	v_and_or_b32 v18, v17, s34, v2
	s_waitcnt lgkmcnt(3)
	v_bfe_u32 v2, v28, 16, 1
	v_add3_u32 v2, v28, v2, s29
	s_waitcnt lgkmcnt(2)
	v_bfe_u32 v17, v30, 16, 1
	ds_read2_b32 v[36:37], v46 offset0:214 offset1:222
	v_lshrrev_b32_e32 v2, 16, v2
	v_add3_u32 v17, v30, v17, s29
	ds_read2_b32 v[38:39], v46 offset0:247 offset1:255
	v_and_or_b32 v19, v17, s34, v2
	s_waitcnt lgkmcnt(3)
	v_bfe_u32 v2, v32, 16, 1
	v_add3_u32 v2, v32, v2, s29
	s_waitcnt lgkmcnt(2)
	v_bfe_u32 v17, v34, 16, 1
	v_lshrrev_b32_e32 v2, 16, v2
	v_add3_u32 v17, v34, v17, s29
	v_and_or_b32 v20, v17, s34, v2
	s_waitcnt lgkmcnt(1)
	v_bfe_u32 v2, v36, 16, 1
	v_add3_u32 v2, v36, v2, s29
	s_waitcnt lgkmcnt(0)
	v_bfe_u32 v17, v38, 16, 1
	v_lshrrev_b32_e32 v2, 16, v2
	v_add3_u32 v17, v38, v17, s29
	v_add_u32_e32 v40, s0, v48
	v_and_or_b32 v21, v17, s34, v2
	v_ashrrev_i32_e32 v41, 31, v40
	v_bfe_u32 v2, v27, 16, 1
	v_lshlrev_b64 v[40:41], 12, v[40:41]
	v_add3_u32 v2, v27, v2, s29
	v_bfe_u32 v17, v23, 16, 1
	v_lshl_add_u64 v[40:41], v[24:25], 0, v[40:41]
	v_lshrrev_b32_e32 v2, 16, v2
	v_add3_u32 v17, v23, v17, s29
	global_store_dwordx4 v[40:41], v[18:21], off
	v_add_u32_e32 v22, s0, v49
	v_ashrrev_i32_e32 v23, 31, v22
	v_and_or_b32 v18, v17, s34, v2
	v_bfe_u32 v2, v29, 16, 1
	v_add3_u32 v2, v29, v2, s29
	v_bfe_u32 v17, v31, 16, 1
	v_lshrrev_b32_e32 v2, 16, v2
	v_add3_u32 v17, v31, v17, s29
	v_and_or_b32 v19, v17, s34, v2
	v_bfe_u32 v2, v33, 16, 1
	v_add3_u32 v2, v33, v2, s29
	v_bfe_u32 v17, v35, 16, 1
	v_lshrrev_b32_e32 v2, 16, v2
	v_add3_u32 v17, v35, v17, s29
	v_and_or_b32 v20, v17, s34, v2
	v_bfe_u32 v2, v37, 16, 1
	v_add3_u32 v2, v37, v2, s29
	v_bfe_u32 v17, v39, 16, 1
	v_lshrrev_b32_e32 v2, 16, v2
	v_add3_u32 v17, v39, v17, s29
	v_lshlrev_b64 v[22:23], 12, v[22:23]
	v_and_or_b32 v21, v17, s34, v2
	v_lshl_add_u64 v[22:23], v[24:25], 0, v[22:23]
	global_store_dwordx4 v[22:23], v[18:21], off
	s_waitcnt lgkmcnt(0)
	s_branch .LBB0_5
